# combination with every hot loop kept at its original 64-byte placement phase: P4 pass-0 reorder, SwiGLU ssq loads hoisted, W_out base tile read six groups ahead, p6 next-row prefetch
# speedup vs baseline: 1.0096x; 1.0096x over previous
.LBB0_432:
	s_mov_b64 s[70:71], 0x80
	s_lshl_b32 s1, s1, 5
	s_add_i32 m0, s11, 0x18000
	v_lshl_add_u64 v[8:9], v[8:9], 0, s[70:71]
	s_lshl_b32 s9, s0, 13
	s_and_b32 s1, s1, 0x60
	s_waitcnt vmcnt(2)
	s_barrier
	global_load_lds_dwordx4 v[8:9], off
	v_lshl_add_u64 v[6:7], v[6:7], 0, s[70:71]
	s_add_i32 m0, s11, 0x1a000
	s_add_i32 s55, s11, 0x8000
	s_add_i32 s56, s11, 0xa000
	global_load_lds_dwordx4 v[6:7], off
	v_lshl_add_u64 v[2:3], v[2:3], 0, s[70:71]
	s_mov_b32 m0, s55
	s_add_u32 s4, s74, 0xb0080
	global_load_lds_dwordx4 v[2:3], off
	v_lshl_add_u64 v[2:3], v[4:5], 0, s[70:71]
	s_mov_b32 m0, s56
	s_addc_u32 s5, s75, 0
	global_load_lds_dwordx4 v[2:3], off
	s_add_i32 m0, s11, 0x1c000
	v_lshl_add_u64 v[2:3], s[4:5], 0, v[158:159]
	global_load_lds_dwordx4 v[2:3], off
	v_lshl_add_u64 v[2:3], s[4:5], 0, v[162:163]
	s_add_i32 m0, s11, 0x1e000
	v_lshl_or_b32 v131, s0, 6, v169
	global_load_lds_dwordx4 v[2:3], off
	v_lshlrev_b32_e32 v2, 6, v169
	s_movk_i32 s0, 0x3c0
	v_lshlrev_b32_e32 v3, 2, v169
	s_cmpk_lt_u32 s8, 0x100
	v_and_or_b32 v2, v2, s0, v207
	v_and_b32_e32 v3, 32, v3
	s_cselect_b64 s[78:79], -1, 0
	s_ashr_i32 s57, s3, 31
	s_ashr_i32 s59, s2, 31
	v_bitop3_b32 v2, v2, s9, v3 bitop3:0xde
	s_waitcnt vmcnt(6)
	s_cmp_lg_u64 s[28:29], 0
	v_add_u16_e32 v3, v173, v179
	v_lshl_or_b32 v149, s1, 7, v208
	s_cselect_b64 s[80:81], -1, 0
	v_lshrrev_b16_e32 v3, 1, v3
	s_add_i32 s61, 0, 0x10000
	s_add_i32 s64, 0, 0x14000
	v_cmp_eq_u32_e64 s[4:5], 0, v210
	v_or_b32_e32 v151, s1, v206
	v_add_lshl_u32 v132, v204, v3, 1
	v_mov_b32_e32 v133, v159
	v_add_lshl_u32 v134, v205, v3, 1
	v_mov_b32_e32 v135, v159
	v_mov_b64_e32 v[136:137], 0xff
	v_add_u32_e32 v153, s61, v149
	v_add_u32_e32 v155, s64, v149
	v_add_u32_e32 v165, 0, v2
	v_mbcnt_hi_u32_b32 v172, -1, v211
	s_barrier
	s_branch .LBB0_435
	s_nop 0
	s_nop 0

.LBB0_944:
	s_cmp_lt_u32 s35, 0x40001
	s_mov_b64 s[64:65], 0
	s_cselect_b64 s[66:67], -1, 0
	s_mov_b64 s[74:75], -1
	s_and_b64 vcc, exec, s[66:67]
	s_cbranch_vccz .LBB0_938
	s_branch .LBB0_943
	s_nop 0
	s_nop 0
	s_nop 0
	s_nop 0
	s_nop 0
	s_nop 0
	s_nop 0

.LBB0_1320:
	s_ashr_i32 s4, s83, 8
	s_cmp_lt_i32 s4, 21
	s_cselect_b32 s5, 0, 11
	s_add_i32 s5, s5, s4
	s_and_b32 s6, s83, 0xff
	s_lshl_b32 s4, s5, 8
	s_ashr_i32 s5, s5, 5
	s_or_b32 s4, s4, s6
	s_mul_i32 s6, s5, 0x2010
	s_and_b32 s7, s4, 0x1fff
	s_ashr_i32 s5, s4, 31
	s_add_i32 s8, s6, s7
	s_lshl_b64 s[6:7], s[4:5], 10
	v_lshl_add_u64 v[74:75], v[64:65], 0, s[6:7]
	s_lshl_b64 s[4:5], s[4:5], 11
	s_add_i32 s8, s8, 16
	global_load_dwordx4 v[74:77], v[74:75], off
	v_lshl_add_u64 v[110:111], v[66:67], 0, s[4:5]
	s_ashr_i32 s9, s8, 31
	v_mad_i64_i32 v[98:99], s[4:5], s8, v72, v[58:59]
	global_load_dwordx4 v[78:81], v[98:99], off
	global_load_dwordx4 v[82:85], v[98:99], off offset:-3648
	global_load_dwordx4 v[86:89], v[98:99], off offset:1024
	global_load_dwordx4 v[90:93], v[98:99], off offset:-2624
	global_load_dwordx4 v[94:97], v[98:99], off offset:2048
	s_nop 0
	global_load_dwordx4 v[98:101], v[98:99], off offset:-1600
	s_lshl_b64 s[4:5], s[8:9], 10
	v_lshl_add_u64 v[102:103], v[60:61], 0, s[4:5]
	v_lshl_add_u64 v[106:107], v[62:63], 0, s[4:5]
	global_load_dwordx4 v[102:105], v[102:103], off
	s_nop 0
	global_load_dwordx4 v[106:109], v[106:107], off
	s_add_i32 s83, s83, s0
	s_sub_i32 s98, s83, s0
	s_cmpk_lt_i32 s83, 0x2a00
	s_cselect_b32 s98, s83, s98
	s_ashr_i32 s4, s98, 8
	s_cmp_lt_i32 s4, 21
	s_cselect_b32 s5, 0, 11
	s_add_i32 s5, s5, s4
	s_and_b32 s6, s98, 0xff
	s_lshl_b32 s4, s5, 8
	s_ashr_i32 s5, s5, 5
	s_or_b32 s4, s4, s6
	s_mul_i32 s6, s5, 0x2010
	s_and_b32 s7, s4, 0x1fff
	s_ashr_i32 s5, s4, 31
	s_add_i32 s8, s6, s7
	s_lshl_b64 s[6:7], s[4:5], 10
	v_lshl_add_u64 v[212:213], v[64:65], 0, s[6:7]
	s_lshl_b64 s[4:5], s[4:5], 11
	s_add_i32 s8, s8, 16
	global_load_dwordx4 v[220:223], v[212:213], off
	s_ashr_i32 s9, s8, 31
	v_mad_i64_i32 v[214:215], s[4:5], s8, v72, v[58:59]
	global_load_dwordx4 v[220:223], v[214:215], off
	global_load_dwordx4 v[220:223], v[214:215], off offset:-3648
	global_load_dwordx4 v[220:223], v[214:215], off offset:1024
	global_load_dwordx4 v[220:223], v[214:215], off offset:-2624
	global_load_dwordx4 v[220:223], v[214:215], off offset:2048
	global_load_dwordx4 v[220:223], v[214:215], off offset:-1600
	s_lshl_b64 s[4:5], s[8:9], 10
	v_lshl_add_u64 v[216:217], v[60:61], 0, s[4:5]
	v_lshl_add_u64 v[218:219], v[62:63], 0, s[4:5]
	global_load_dwordx4 v[220:223], v[216:217], off
	global_load_dwordx4 v[220:223], v[218:219], off
	s_cmpk_lt_i32 s83, 0x2a00
	s_waitcnt vmcnt(16)
	v_and_b32_e32 v125, 0xffff0000, v79
	v_lshlrev_b32_e32 v116, 16, v74
	v_and_b32_e32 v117, 0xffff0000, v74
	v_add_f32_e32 v73, 0, v116
	v_lshlrev_b32_e32 v112, 16, v77
	v_and_b32_e32 v113, 0xffff0000, v77
	v_lshlrev_b32_e32 v114, 16, v76
	v_and_b32_e32 v115, 0xffff0000, v76
	v_lshlrev_b32_e32 v76, 16, v75
	v_and_b32_e32 v77, 0xffff0000, v75
	v_and_b32_e32 v75, 0xffff0000, v78
	v_lshlrev_b32_e32 v74, 16, v78
	s_waitcnt vmcnt(15)
	v_and_b32_e32 v119, 0xffff0000, v82
	v_lshlrev_b32_e32 v118, 16, v82
	s_waitcnt vmcnt(14)
	v_and_b32_e32 v121, 0xffff0000, v86
	v_lshlrev_b32_e32 v120, 16, v86
	s_waitcnt vmcnt(13)
	v_and_b32_e32 v123, 0xffff0000, v90
	v_lshlrev_b32_e32 v122, 16, v90
	v_lshlrev_b32_e32 v124, 16, v79
	v_and_b32_e32 v79, 0xffff0000, v83
	v_lshlrev_b32_e32 v78, 16, v83
	v_and_b32_e32 v83, 0xffff0000, v87
	v_lshlrev_b32_e32 v82, 16, v87
	v_and_b32_e32 v87, 0xffff0000, v91
	v_lshlrev_b32_e32 v86, 16, v91
	v_and_b32_e32 v91, 0xffff0000, v80
	v_lshlrev_b32_e32 v90, 16, v80
	v_and_b32_e32 v127, 0xffff0000, v84
	v_lshlrev_b32_e32 v126, 16, v84
	v_and_b32_e32 v129, 0xffff0000, v88
	v_lshlrev_b32_e32 v128, 16, v88
	v_and_b32_e32 v131, 0xffff0000, v92
	v_lshlrev_b32_e32 v130, 16, v92
	v_and_b32_e32 v133, 0xffff0000, v81
	v_lshlrev_b32_e32 v132, 16, v81
	v_and_b32_e32 v81, 0xffff0000, v85
	v_lshlrev_b32_e32 v80, 16, v85
	v_and_b32_e32 v85, 0xffff0000, v89
	v_lshlrev_b32_e32 v84, 16, v89
	v_and_b32_e32 v89, 0xffff0000, v93
	v_lshlrev_b32_e32 v88, 16, v93
	s_waitcnt vmcnt(12)
	v_lshlrev_b32_e32 v92, 16, v97
	v_and_b32_e32 v93, 0xffff0000, v97
	s_waitcnt vmcnt(11)
	v_lshlrev_b32_e32 v134, 16, v101
	v_and_b32_e32 v135, 0xffff0000, v101
	v_lshlrev_b32_e32 v136, 16, v96
	v_and_b32_e32 v137, 0xffff0000, v96
	v_lshlrev_b32_e32 v96, 16, v100
	v_and_b32_e32 v97, 0xffff0000, v100
	v_lshlrev_b32_e32 v100, 16, v95
	v_and_b32_e32 v101, 0xffff0000, v95
	v_lshlrev_b32_e32 v138, 16, v99
	v_and_b32_e32 v139, 0xffff0000, v99
	v_add_f32_e32 v73, v73, v117
	v_lshlrev_b32_e32 v140, 16, v94
	v_and_b32_e32 v141, 0xffff0000, v94
	v_lshlrev_b32_e32 v94, 16, v98
	v_and_b32_e32 v95, 0xffff0000, v98
	v_pk_add_f32 v[98:99], v[118:119], v[74:75] neg_lo:[0,1] neg_hi:[0,1]
	v_pk_add_f32 v[118:119], v[122:123], v[120:121] neg_lo:[0,1] neg_hi:[0,1]
	v_pk_add_f32 v[86:87], v[86:87], v[82:83] neg_lo:[0,1] neg_hi:[0,1]
	v_pk_add_f32 v[122:123], v[126:127], v[90:91] neg_lo:[0,1] neg_hi:[0,1]
	v_pk_add_f32 v[126:127], v[130:131], v[128:129] neg_lo:[0,1] neg_hi:[0,1]
	v_pk_add_f32 v[88:89], v[88:89], v[84:85] neg_lo:[0,1] neg_hi:[0,1]
	v_pk_add_f32 v[130:131], v[138:139], v[100:101] neg_lo:[0,1] neg_hi:[0,1]
	s_waitcnt vmcnt(10)
	v_and_b32_e32 v139, 0xffff0000, v102
	v_lshlrev_b32_e32 v138, 16, v102
	v_add_f32_e32 v73, v73, v76
	v_pk_fma_f32 v[74:75], v[54:55], v[98:99], v[74:75]
	v_pk_fma_f32 v[98:99], v[46:47], v[118:119], v[120:121]
	v_pk_fma_f32 v[82:83], v[48:49], v[86:87], v[82:83]
	v_and_b32_e32 v87, 0xffff0000, v104
	v_lshlrev_b32_e32 v86, 16, v104
	v_pk_fma_f32 v[90:91], v[50:51], v[122:123], v[90:91]
	v_and_b32_e32 v121, 0xffff0000, v105
	v_lshlrev_b32_e32 v120, 16, v105
	v_pk_fma_f32 v[84:85], v[44:45], v[88:89], v[84:85]
	s_waitcnt vmcnt(9)
	v_lshlrev_b32_e32 v88, 16, v109
	v_and_b32_e32 v89, 0xffff0000, v109
	v_lshlrev_b32_e32 v104, 16, v108
	v_and_b32_e32 v105, 0xffff0000, v108
	v_lshlrev_b32_e32 v108, 16, v107
	v_and_b32_e32 v109, 0xffff0000, v107
	v_lshlrev_b32_e32 v122, 16, v106
	v_and_b32_e32 v123, 0xffff0000, v106
	v_pk_add_f32 v[106:107], v[138:139], -1.0 op_sel_hi:[1,0]
	v_add_f32_e32 v73, v73, v77
	v_and_b32_e32 v119, 0xffff0000, v103
	v_lshlrev_b32_e32 v118, 16, v103
	v_pk_fma_f32 v[106:107], v[38:39], v[106:107], 1.0 op_sel_hi:[1,1,0]
	v_add_f32_e32 v73, v73, v114
	v_pk_add_f32 v[118:119], v[118:119], -1.0 op_sel_hi:[1,0]
	v_pk_add_f32 v[120:121], v[120:121], -1.0 op_sel_hi:[1,0]
	v_pk_mul_f32 v[98:99], v[98:99], v[106:107]
	v_add_f32_e32 v73, v73, v115
	v_pk_add_f32 v[78:79], v[78:79], v[124:125] neg_lo:[0,1] neg_hi:[0,1]
	v_pk_add_f32 v[80:81], v[80:81], v[132:133] neg_lo:[0,1] neg_hi:[0,1]
	v_pk_fma_f32 v[118:119], v[40:41], v[118:119], 1.0 op_sel_hi:[1,1,0]
	v_pk_fma_f32 v[120:121], v[32:33], v[120:121], 1.0 op_sel_hi:[1,1,0]
	v_pk_mul_f32 v[74:75], v[74:75], v[98:99]
	v_add_f32_e32 v73, v73, v112
	v_pk_fma_f32 v[78:79], v[56:57], v[78:79], v[124:125]
	v_pk_fma_f32 v[80:81], v[52:53], v[80:81], v[132:133]
	v_pk_add_f32 v[86:87], v[86:87], -1.0 op_sel_hi:[1,0]
	v_pk_mul_f32 v[82:83], v[82:83], v[118:119]
	v_pk_mul_f32 v[84:85], v[84:85], v[120:121]
	v_pk_mul_f32 v[74:75], v[34:35], v[74:75]
	v_add_f32_e32 v73, v73, v113
	v_pk_fma_f32 v[102:103], v[42:43], v[126:127], v[128:129]
	v_pk_fma_f32 v[86:87], v[30:31], v[86:87], 1.0 op_sel_hi:[1,1,0]
	v_pk_mul_f32 v[78:79], v[78:79], v[82:83]
	v_pk_mul_f32 v[80:81], v[80:81], v[84:85]
	v_add_f32_e32 v74, 0, v74
	ds_bpermute_b32 v84, v68, v73
	v_pk_mul_f32 v[86:87], v[102:103], v[86:87]
	v_pk_mul_f32 v[78:79], v[36:37], v[78:79]
	v_add_f32_e32 v74, v75, v74
	v_pk_mul_f32 v[82:83], v[90:91], v[86:87]
	v_add_f32_e32 v74, v78, v74
	v_pk_mul_f32 v[82:83], v[26:27], v[82:83]
	v_add_f32_e32 v74, v79, v74
	v_add_f32_e32 v74, v82, v74
	v_pk_mul_f32 v[80:81], v[28:29], v[80:81]
	v_add_f32_e32 v74, v83, v74
	s_waitcnt lgkmcnt(0)
	v_add_f32_e32 v73, v73, v84
	v_add_f32_e32 v74, v80, v74
	ds_bpermute_b32 v75, v69, v73
	v_add_f32_e32 v74, v81, v74
	ds_bpermute_b32 v78, v68, v74
	v_pk_add_f32 v[96:97], v[96:97], v[136:137] neg_lo:[0,1] neg_hi:[0,1]
	v_pk_add_f32 v[94:95], v[94:95], v[140:141] neg_lo:[0,1] neg_hi:[0,1]
	s_waitcnt lgkmcnt(1)
	v_add_f32_e32 v73, v73, v75
	ds_bpermute_b32 v75, v70, v73
	s_waitcnt lgkmcnt(1)
	v_add_f32_e32 v78, v74, v78
	ds_bpermute_b32 v79, v69, v78
	v_pk_add_f32 v[134:135], v[134:135], v[92:93] neg_lo:[0,1] neg_hi:[0,1]
	v_pk_fma_f32 v[96:97], v[6:7], v[96:97], v[136:137]
	s_waitcnt lgkmcnt(1)
	v_add_f32_e32 v73, v73, v75
	v_mul_f32_e32 v74, 0x3c800000, v73
	s_waitcnt lgkmcnt(0)
	v_add_f32_e32 v73, v78, v79
	v_pk_add_f32 v[78:79], v[116:117], v[74:75] op_sel_hi:[1,0] neg_lo:[0,1] neg_hi:[0,1]
	v_pk_add_f32 v[76:77], v[76:77], v[74:75] op_sel_hi:[1,0] neg_lo:[0,1] neg_hi:[0,1]
	ds_bpermute_b32 v98, v70, v73
	v_pk_mul_f32 v[82:83], v[78:79], v[78:79]
	v_pk_mul_f32 v[84:85], v[76:77], v[76:77]
	v_add_f32_e32 v82, v82, v83
	v_pk_add_f32 v[80:81], v[114:115], v[74:75] op_sel_hi:[1,0] neg_lo:[0,1] neg_hi:[0,1]
	v_add_f32_e32 v82, v84, v82
	v_pk_mul_f32 v[86:87], v[80:81], v[80:81]
	v_add_f32_e32 v82, v85, v82
	v_pk_add_f32 v[74:75], v[112:113], v[74:75] op_sel_hi:[1,0] neg_lo:[0,1] neg_hi:[0,1]
	v_add_f32_e32 v83, v86, v82
	v_pk_mul_f32 v[90:91], v[74:75], v[74:75]
	s_waitcnt lgkmcnt(0)
	v_add_f32_e32 v82, v73, v98
	v_add_f32_e32 v73, v87, v83
	v_add_f32_e32 v73, v90, v73
	v_add_f32_e32 v73, v91, v73
	ds_bpermute_b32 v83, v68, v73
	v_pk_fma_f32 v[100:101], v[4:5], v[130:131], v[100:101]
	v_pk_fma_f32 v[94:95], v[2:3], v[94:95], v[140:141]
	v_pk_fma_f32 v[92:93], v[8:9], v[134:135], v[92:93]
	s_waitcnt lgkmcnt(0)
	v_add_f32_e32 v73, v73, v83
	ds_bpermute_b32 v83, v69, v73
	s_waitcnt lgkmcnt(0)
	v_add_f32_e32 v73, v73, v83
	ds_bpermute_b32 v83, v70, v73
	s_waitcnt lgkmcnt(0)
	v_add_f32_e32 v73, v73, v83
	v_fmamk_f32 v73, v73, 0x3c800000, v71
	v_mul_f32_e32 v83, 0x4b800000, v73
	v_cmp_gt_f32_e32 vcc, s1, v73
	s_nop 1
	v_cndmask_b32_e32 v73, v73, v83, vcc
	v_rsq_f32_e32 v73, v73
	s_nop 0
	v_mul_f32_e32 v83, 0x45800000, v73
	v_cndmask_b32_e32 v84, v73, v83, vcc
	v_pk_mul_f32 v[78:79], v[78:79], v[84:85] op_sel_hi:[1,0]
	v_pk_mul_f32 v[76:77], v[76:77], v[84:85] op_sel_hi:[1,0]
	v_pk_mul_f32 v[80:81], v[80:81], v[84:85] op_sel_hi:[1,0]
	v_pk_mul_f32 v[74:75], v[74:75], v[84:85] op_sel_hi:[1,0]
	v_pk_fma_f32 v[78:79], v[18:19], v[78:79], v[22:23]
	v_pk_fma_f32 v[76:77], v[20:21], v[76:77], v[24:25]
	v_pk_fma_f32 v[80:81], v[10:11], v[80:81], v[14:15]
	v_pk_fma_f32 v[74:75], v[12:13], v[74:75], v[16:17]
	v_pk_fma_f32 v[78:79], v[94:95], v[82:83], v[78:79] op_sel_hi:[1,0,1]
	v_pk_fma_f32 v[76:77], v[100:101], v[82:83], v[76:77] op_sel_hi:[1,0,1]
	v_pk_fma_f32 v[80:81], v[96:97], v[82:83], v[80:81] op_sel_hi:[1,0,1]
	v_pk_fma_f32 v[74:75], v[92:93], v[82:83], v[74:75] op_sel_hi:[1,0,1]
	v_pk_mul_f32 v[78:79], v[78:79], v[122:123]
	v_pk_mul_f32 v[76:77], v[76:77], v[108:109]
	v_pk_mul_f32 v[80:81], v[80:81], v[104:105]
	v_pk_mul_f32 v[82:83], v[74:75], v[88:89]
	v_cvt_pk_bf16_f32 v74, v78, v79
	v_cvt_pk_bf16_f32 v75, v76, v77
	v_cvt_pk_bf16_f32 v76, v80, v81
	v_cvt_pk_bf16_f32 v77, v82, v83
	global_store_dwordx4 v[110:111], v[74:77], off offset:1024
	s_cbranch_scc1 .LBB0_1320

.LBB0_1378:
	s_mov_b64 s[20:21], 0x80
	s_lshl_b32 s1, s1, 5
	s_add_i32 m0, s11, 0x18000
	v_lshl_add_u64 v[8:9], v[8:9], 0, s[20:21]
	s_lshl_b32 s5, s0, 13
	s_and_b32 s1, s1, 0x60
	s_waitcnt vmcnt(2)
	s_barrier
	global_load_lds_dwordx4 v[8:9], off
	v_lshl_add_u64 v[4:5], v[4:5], 0, s[20:21]
	s_add_i32 m0, s11, 0x1a000
	s_add_i32 s85, s11, 0x8000
	s_add_i32 s86, s11, 0xa000
	global_load_lds_dwordx4 v[4:5], off
	v_lshl_add_u64 v[2:3], v[2:3], 0, s[20:21]
	s_mov_b32 m0, s85
	s_add_u32 s6, s78, 0x40080
	global_load_lds_dwordx4 v[2:3], off
	v_lshl_add_u64 v[2:3], v[6:7], 0, s[20:21]
	s_mov_b32 m0, s86
	s_addc_u32 s7, s79, 0
	global_load_lds_dwordx4 v[2:3], off
	s_add_i32 m0, s11, 0x1c000
	v_lshl_add_u64 v[2:3], s[6:7], 0, v[148:149]
	global_load_lds_dwordx4 v[2:3], off
	v_lshl_add_u64 v[2:3], s[6:7], 0, v[152:153]
	s_add_i32 m0, s11, 0x1e000
	v_lshl_or_b32 v159, s0, 6, v169
	global_load_lds_dwordx4 v[2:3], off
	s_movk_i32 s0, 0x3c0
	v_lshlrev_b32_e32 v3, 2, v169
	v_and_or_b32 v2, v155, s0, v207
	v_and_b32_e32 v3, 32, v3
	v_bitop3_b32 v2, v2, s5, v3 bitop3:0xde
	v_lshlrev_b32_e32 v3, 8, v0
	v_and_b32_e32 v3, 0x18000, v3
	v_lshlrev_b32_e32 v4, 11, v1
	s_cmpk_lt_u32 s4, 0x100
	v_or3_b32 v3, v173, v3, v4
	s_cselect_b64 s[22:23], -1, 0
	s_ashr_i32 s87, s80, 31
	s_waitcnt vmcnt(0)
	v_add_u32_e32 v130, v3, v179
	v_lshlrev_b32_e32 v3, 4, v200
	s_waitcnt vmcnt(6)
	s_cmp_lg_u64 s[28:29], 0
	v_and_b32_e32 v3, 0x38000, v3
	v_lshl_or_b32 v161, s1, 7, v208
	s_cselect_b64 s[24:25], -1, 0
	v_or3_b32 v3, v173, v3, v4
	s_add_i32 s88, 0, 0x10000
	s_add_i32 s89, 0, 0x14000
	v_cmp_eq_u32_e64 s[4:5], 0, v210
	v_or_b32_e32 v163, s1, v206
	v_mov_b32_e32 v131, v149
	v_add_u32_e32 v132, v3, v179
	v_mov_b32_e32 v133, v149
	v_mov_b64_e32 v[134:135], 0xa8
	v_mov_b64_e32 v[136:137], 0xa7
	v_add_u32_e32 v165, s88, v161
	v_add_u32_e32 v168, s89, v161
	v_add_u32_e32 v171, 0, v2
	s_mov_b64 s[58:59], 0x48000
	s_mov_b64 s[60:61], 0x50000
	s_mov_b64 s[62:63], 0x58000
	s_barrier
	s_branch .LBB0_1381
	s_nop 0
	s_nop 0
	s_nop 0
	s_nop 0
	s_nop 0
	s_nop 0
	s_nop 0
	s_nop 0
	s_nop 0
	s_nop 0
	s_nop 0
	s_nop 0
	s_nop 0
	s_nop 0
	s_nop 0

.LBB0_1575:
	s_cmp_lt_u32 s35, 0x40001
	s_mov_b64 s[24:25], 0
	s_cselect_b64 s[30:31], -1, 0
	s_mov_b64 s[58:59], -1
	s_and_b64 vcc, exec, s[30:31]
	s_cbranch_vccz .LBB0_1569
	s_branch .LBB0_1574
	s_nop 0
	s_nop 0
	s_nop 0
	s_nop 0
	s_nop 0
	s_nop 0
	s_nop 0
	s_nop 0

.LBB0_1585:
	s_ashr_i32 s1, s34, 8
	s_cmp_lt_i32 s1, 11
	s_cselect_b32 s4, 21, 42
	s_add_i32 s4, s4, s1
	s_and_b32 s5, s34, 0xff
	s_lshl_b32 s1, s4, 8
	s_ashr_i32 s6, s4, 5
	s_or_b32 s4, s1, s5
	s_mul_i32 s1, s6, 0x2010
	s_and_b32 s6, s4, 0x1fff
	s_ashr_i32 s5, s4, 31
	s_add_i32 s1, s1, s6
	s_lshl_b64 s[6:7], s[4:5], 10
	v_lshl_add_u64 v[74:75], v[64:65], 0, s[6:7]
	s_lshl_b64 s[4:5], s[4:5], 11
	s_add_i32 s8, s1, 16
	global_load_dwordx4 v[74:77], v[74:75], off
	v_lshl_add_u64 v[110:111], v[66:67], 0, s[4:5]
	s_ashr_i32 s9, s8, 31
	v_mad_i64_i32 v[102:103], s[4:5], s8, v72, v[58:59]
	global_load_dwordx4 v[78:81], v[102:103], off
	global_load_dwordx4 v[82:85], v[102:103], off offset:-3648
	global_load_dwordx4 v[86:89], v[102:103], off offset:1024
	global_load_dwordx4 v[90:93], v[102:103], off offset:-2624
	global_load_dwordx4 v[94:97], v[102:103], off offset:2048
	global_load_dwordx4 v[98:101], v[102:103], off offset:-1600
	s_lshl_b64 s[4:5], s[8:9], 10
	v_lshl_add_u64 v[102:103], v[60:61], 0, s[4:5]
	v_lshl_add_u64 v[106:107], v[62:63], 0, s[4:5]
	global_load_dwordx4 v[102:105], v[102:103], off
	s_nop 0
	global_load_dwordx4 v[106:109], v[106:107], off
	s_add_i32 s34, s34, s88
	s_sub_i32 s98, s34, s88
	s_cmpk_lt_i32 s34, 0x1600
	s_cselect_b32 s98, s34, s98
	s_ashr_i32 s1, s98, 8
	s_cmp_lt_i32 s1, 11
	s_cselect_b32 s4, 21, 42
	s_add_i32 s4, s4, s1
	s_and_b32 s5, s98, 0xff
	s_lshl_b32 s1, s4, 8
	s_ashr_i32 s6, s4, 5
	s_or_b32 s4, s1, s5
	s_mul_i32 s1, s6, 0x2010
	s_and_b32 s6, s4, 0x1fff
	s_ashr_i32 s5, s4, 31
	s_add_i32 s1, s1, s6
	s_lshl_b64 s[6:7], s[4:5], 10
	v_lshl_add_u64 v[212:213], v[64:65], 0, s[6:7]
	s_lshl_b64 s[4:5], s[4:5], 11
	s_add_i32 s8, s1, 16
	global_load_dwordx4 v[220:223], v[212:213], off
	s_ashr_i32 s9, s8, 31
	v_mad_i64_i32 v[214:215], s[4:5], s8, v72, v[58:59]
	global_load_dwordx4 v[220:223], v[214:215], off
	global_load_dwordx4 v[220:223], v[214:215], off offset:-3648
	global_load_dwordx4 v[220:223], v[214:215], off offset:1024
	global_load_dwordx4 v[220:223], v[214:215], off offset:-2624
	global_load_dwordx4 v[220:223], v[214:215], off offset:2048
	global_load_dwordx4 v[220:223], v[214:215], off offset:-1600
	s_lshl_b64 s[4:5], s[8:9], 10
	v_lshl_add_u64 v[216:217], v[60:61], 0, s[4:5]
	v_lshl_add_u64 v[218:219], v[62:63], 0, s[4:5]
	global_load_dwordx4 v[220:223], v[216:217], off
	global_load_dwordx4 v[220:223], v[218:219], off
	s_cmpk_lt_i32 s34, 0x1600
	s_waitcnt vmcnt(16)
	v_and_b32_e32 v125, 0xffff0000, v79
	v_lshlrev_b32_e32 v116, 16, v74
	v_and_b32_e32 v117, 0xffff0000, v74
	v_add_f32_e32 v73, 0, v116
	v_lshlrev_b32_e32 v112, 16, v77
	v_and_b32_e32 v113, 0xffff0000, v77
	v_lshlrev_b32_e32 v114, 16, v76
	v_and_b32_e32 v115, 0xffff0000, v76
	v_lshlrev_b32_e32 v76, 16, v75
	v_and_b32_e32 v77, 0xffff0000, v75
	v_and_b32_e32 v75, 0xffff0000, v78
	v_lshlrev_b32_e32 v74, 16, v78
	s_waitcnt vmcnt(15)
	v_and_b32_e32 v119, 0xffff0000, v82
	v_lshlrev_b32_e32 v118, 16, v82
	s_waitcnt vmcnt(14)
	v_and_b32_e32 v121, 0xffff0000, v86
	v_lshlrev_b32_e32 v120, 16, v86
	s_waitcnt vmcnt(13)
	v_and_b32_e32 v123, 0xffff0000, v90
	v_lshlrev_b32_e32 v122, 16, v90
	v_lshlrev_b32_e32 v124, 16, v79
	v_and_b32_e32 v79, 0xffff0000, v83
	v_lshlrev_b32_e32 v78, 16, v83
	v_and_b32_e32 v83, 0xffff0000, v87
	v_lshlrev_b32_e32 v82, 16, v87
	v_and_b32_e32 v87, 0xffff0000, v91
	v_lshlrev_b32_e32 v86, 16, v91
	v_and_b32_e32 v91, 0xffff0000, v80
	v_lshlrev_b32_e32 v90, 16, v80
	v_and_b32_e32 v127, 0xffff0000, v84
	v_lshlrev_b32_e32 v126, 16, v84
	v_and_b32_e32 v129, 0xffff0000, v88
	v_lshlrev_b32_e32 v128, 16, v88
	v_and_b32_e32 v131, 0xffff0000, v92
	v_lshlrev_b32_e32 v130, 16, v92
	v_and_b32_e32 v133, 0xffff0000, v81
	v_lshlrev_b32_e32 v132, 16, v81
	v_and_b32_e32 v81, 0xffff0000, v85
	v_lshlrev_b32_e32 v80, 16, v85
	v_and_b32_e32 v85, 0xffff0000, v89
	v_lshlrev_b32_e32 v84, 16, v89
	v_and_b32_e32 v89, 0xffff0000, v93
	v_lshlrev_b32_e32 v88, 16, v93
	s_waitcnt vmcnt(12)
	v_lshlrev_b32_e32 v92, 16, v97
	v_and_b32_e32 v93, 0xffff0000, v97
	s_waitcnt vmcnt(11)
	v_lshlrev_b32_e32 v134, 16, v101
	v_and_b32_e32 v135, 0xffff0000, v101
	v_lshlrev_b32_e32 v136, 16, v96
	v_and_b32_e32 v137, 0xffff0000, v96
	v_lshlrev_b32_e32 v96, 16, v100
	v_and_b32_e32 v97, 0xffff0000, v100
	v_lshlrev_b32_e32 v100, 16, v95
	v_and_b32_e32 v101, 0xffff0000, v95
	v_lshlrev_b32_e32 v138, 16, v99
	v_and_b32_e32 v139, 0xffff0000, v99
	v_add_f32_e32 v73, v73, v117
	v_lshlrev_b32_e32 v140, 16, v94
	v_and_b32_e32 v141, 0xffff0000, v94
	v_lshlrev_b32_e32 v94, 16, v98
	v_and_b32_e32 v95, 0xffff0000, v98
	v_pk_add_f32 v[98:99], v[118:119], v[74:75] neg_lo:[0,1] neg_hi:[0,1]
	v_pk_add_f32 v[118:119], v[122:123], v[120:121] neg_lo:[0,1] neg_hi:[0,1]
	v_pk_add_f32 v[86:87], v[86:87], v[82:83] neg_lo:[0,1] neg_hi:[0,1]
	v_pk_add_f32 v[122:123], v[126:127], v[90:91] neg_lo:[0,1] neg_hi:[0,1]
	v_pk_add_f32 v[126:127], v[130:131], v[128:129] neg_lo:[0,1] neg_hi:[0,1]
	v_pk_add_f32 v[88:89], v[88:89], v[84:85] neg_lo:[0,1] neg_hi:[0,1]
	v_pk_add_f32 v[130:131], v[138:139], v[100:101] neg_lo:[0,1] neg_hi:[0,1]
	s_waitcnt vmcnt(10)
	v_and_b32_e32 v139, 0xffff0000, v102
	v_lshlrev_b32_e32 v138, 16, v102
	v_add_f32_e32 v73, v73, v76
	v_pk_fma_f32 v[74:75], v[54:55], v[98:99], v[74:75]
	v_pk_fma_f32 v[98:99], v[46:47], v[118:119], v[120:121]
	v_pk_fma_f32 v[82:83], v[48:49], v[86:87], v[82:83]
	v_and_b32_e32 v87, 0xffff0000, v104
	v_lshlrev_b32_e32 v86, 16, v104
	v_pk_fma_f32 v[90:91], v[50:51], v[122:123], v[90:91]
	v_and_b32_e32 v121, 0xffff0000, v105
	v_lshlrev_b32_e32 v120, 16, v105
	v_pk_fma_f32 v[84:85], v[44:45], v[88:89], v[84:85]
	s_waitcnt vmcnt(9)
	v_lshlrev_b32_e32 v88, 16, v109
	v_and_b32_e32 v89, 0xffff0000, v109
	v_lshlrev_b32_e32 v104, 16, v108
	v_and_b32_e32 v105, 0xffff0000, v108
	v_lshlrev_b32_e32 v108, 16, v107
	v_and_b32_e32 v109, 0xffff0000, v107
	v_lshlrev_b32_e32 v122, 16, v106
	v_and_b32_e32 v123, 0xffff0000, v106
	v_pk_add_f32 v[106:107], v[138:139], -1.0 op_sel_hi:[1,0]
	v_add_f32_e32 v73, v73, v77
	v_and_b32_e32 v119, 0xffff0000, v103
	v_lshlrev_b32_e32 v118, 16, v103
	v_pk_fma_f32 v[106:107], v[38:39], v[106:107], 1.0 op_sel_hi:[1,1,0]
	v_add_f32_e32 v73, v73, v114
	v_pk_add_f32 v[118:119], v[118:119], -1.0 op_sel_hi:[1,0]
	v_pk_add_f32 v[120:121], v[120:121], -1.0 op_sel_hi:[1,0]
	v_pk_mul_f32 v[98:99], v[98:99], v[106:107]
	v_add_f32_e32 v73, v73, v115
	v_pk_add_f32 v[78:79], v[78:79], v[124:125] neg_lo:[0,1] neg_hi:[0,1]
	v_pk_add_f32 v[80:81], v[80:81], v[132:133] neg_lo:[0,1] neg_hi:[0,1]
	v_pk_fma_f32 v[118:119], v[40:41], v[118:119], 1.0 op_sel_hi:[1,1,0]
	v_pk_fma_f32 v[120:121], v[32:33], v[120:121], 1.0 op_sel_hi:[1,1,0]
	v_pk_mul_f32 v[74:75], v[74:75], v[98:99]
	v_add_f32_e32 v73, v73, v112
	v_pk_fma_f32 v[78:79], v[56:57], v[78:79], v[124:125]
	v_pk_fma_f32 v[80:81], v[52:53], v[80:81], v[132:133]
	v_pk_add_f32 v[86:87], v[86:87], -1.0 op_sel_hi:[1,0]
	v_pk_mul_f32 v[82:83], v[82:83], v[118:119]
	v_pk_mul_f32 v[84:85], v[84:85], v[120:121]
	v_pk_mul_f32 v[74:75], v[34:35], v[74:75]
	v_add_f32_e32 v73, v73, v113
	v_pk_fma_f32 v[102:103], v[42:43], v[126:127], v[128:129]
	v_pk_fma_f32 v[86:87], v[30:31], v[86:87], 1.0 op_sel_hi:[1,1,0]
	v_pk_mul_f32 v[78:79], v[78:79], v[82:83]
	v_pk_mul_f32 v[80:81], v[80:81], v[84:85]
	v_add_f32_e32 v74, 0, v74
	ds_bpermute_b32 v84, v68, v73
	v_pk_mul_f32 v[86:87], v[102:103], v[86:87]
	v_pk_mul_f32 v[78:79], v[36:37], v[78:79]
	v_add_f32_e32 v74, v75, v74
	v_pk_mul_f32 v[82:83], v[90:91], v[86:87]
	v_add_f32_e32 v74, v78, v74
	v_pk_mul_f32 v[82:83], v[26:27], v[82:83]
	v_add_f32_e32 v74, v79, v74
	v_add_f32_e32 v74, v82, v74
	v_pk_mul_f32 v[80:81], v[28:29], v[80:81]
	v_add_f32_e32 v74, v83, v74
	s_waitcnt lgkmcnt(0)
	v_add_f32_e32 v73, v73, v84
	v_add_f32_e32 v74, v80, v74
	ds_bpermute_b32 v75, v69, v73
	v_add_f32_e32 v74, v81, v74
	ds_bpermute_b32 v78, v68, v74
	v_pk_add_f32 v[96:97], v[96:97], v[136:137] neg_lo:[0,1] neg_hi:[0,1]
	v_pk_add_f32 v[94:95], v[94:95], v[140:141] neg_lo:[0,1] neg_hi:[0,1]
	s_waitcnt lgkmcnt(1)
	v_add_f32_e32 v73, v73, v75
	ds_bpermute_b32 v75, v70, v73
	s_waitcnt lgkmcnt(1)
	v_add_f32_e32 v78, v74, v78
	ds_bpermute_b32 v79, v69, v78
	v_pk_add_f32 v[134:135], v[134:135], v[92:93] neg_lo:[0,1] neg_hi:[0,1]
	v_pk_fma_f32 v[96:97], v[6:7], v[96:97], v[136:137]
	s_waitcnt lgkmcnt(1)
	v_add_f32_e32 v73, v73, v75
	v_mul_f32_e32 v74, 0x3c800000, v73
	s_waitcnt lgkmcnt(0)
	v_add_f32_e32 v73, v78, v79
	v_pk_add_f32 v[78:79], v[116:117], v[74:75] op_sel_hi:[1,0] neg_lo:[0,1] neg_hi:[0,1]
	v_pk_add_f32 v[76:77], v[76:77], v[74:75] op_sel_hi:[1,0] neg_lo:[0,1] neg_hi:[0,1]
	ds_bpermute_b32 v98, v70, v73
	v_pk_mul_f32 v[82:83], v[78:79], v[78:79]
	v_pk_mul_f32 v[84:85], v[76:77], v[76:77]
	v_add_f32_e32 v82, v82, v83
	v_pk_add_f32 v[80:81], v[114:115], v[74:75] op_sel_hi:[1,0] neg_lo:[0,1] neg_hi:[0,1]
	v_add_f32_e32 v82, v84, v82
	v_pk_mul_f32 v[86:87], v[80:81], v[80:81]
	v_add_f32_e32 v82, v85, v82
	v_pk_add_f32 v[74:75], v[112:113], v[74:75] op_sel_hi:[1,0] neg_lo:[0,1] neg_hi:[0,1]
	v_add_f32_e32 v83, v86, v82
	v_pk_mul_f32 v[90:91], v[74:75], v[74:75]
	s_waitcnt lgkmcnt(0)
	v_add_f32_e32 v82, v73, v98
	v_add_f32_e32 v73, v87, v83
	v_add_f32_e32 v73, v90, v73
	v_add_f32_e32 v73, v91, v73
	ds_bpermute_b32 v83, v68, v73
	v_pk_fma_f32 v[100:101], v[4:5], v[130:131], v[100:101]
	v_pk_fma_f32 v[94:95], v[2:3], v[94:95], v[140:141]
	v_pk_fma_f32 v[92:93], v[8:9], v[134:135], v[92:93]
	s_waitcnt lgkmcnt(0)
	v_add_f32_e32 v73, v73, v83
	ds_bpermute_b32 v83, v69, v73
	s_waitcnt lgkmcnt(0)
	v_add_f32_e32 v73, v73, v83
	ds_bpermute_b32 v83, v70, v73
	s_waitcnt lgkmcnt(0)
	v_add_f32_e32 v73, v73, v83
	v_fmamk_f32 v73, v73, 0x3c800000, v71
	v_mul_f32_e32 v83, 0x4b800000, v73
	v_cmp_gt_f32_e32 vcc, s0, v73
	s_nop 1
	v_cndmask_b32_e32 v73, v73, v83, vcc
	v_rsq_f32_e32 v73, v73
	s_nop 0
	v_mul_f32_e32 v83, 0x45800000, v73
	v_cndmask_b32_e32 v84, v73, v83, vcc
	v_pk_mul_f32 v[78:79], v[78:79], v[84:85] op_sel_hi:[1,0]
	v_pk_mul_f32 v[76:77], v[76:77], v[84:85] op_sel_hi:[1,0]
	v_pk_mul_f32 v[80:81], v[80:81], v[84:85] op_sel_hi:[1,0]
	v_pk_mul_f32 v[74:75], v[74:75], v[84:85] op_sel_hi:[1,0]
	v_pk_fma_f32 v[78:79], v[18:19], v[78:79], v[22:23]
	v_pk_fma_f32 v[76:77], v[20:21], v[76:77], v[24:25]
	v_pk_fma_f32 v[80:81], v[10:11], v[80:81], v[14:15]
	v_pk_fma_f32 v[74:75], v[12:13], v[74:75], v[16:17]
	v_pk_fma_f32 v[78:79], v[94:95], v[82:83], v[78:79] op_sel_hi:[1,0,1]
	v_pk_fma_f32 v[76:77], v[100:101], v[82:83], v[76:77] op_sel_hi:[1,0,1]
	v_pk_fma_f32 v[80:81], v[96:97], v[82:83], v[80:81] op_sel_hi:[1,0,1]
	v_pk_fma_f32 v[74:75], v[92:93], v[82:83], v[74:75] op_sel_hi:[1,0,1]
	v_pk_mul_f32 v[78:79], v[78:79], v[122:123]
	v_pk_mul_f32 v[76:77], v[76:77], v[108:109]
	v_pk_mul_f32 v[80:81], v[80:81], v[104:105]
	v_pk_mul_f32 v[82:83], v[74:75], v[88:89]
	v_cvt_pk_bf16_f32 v74, v78, v79
	v_cvt_pk_bf16_f32 v75, v76, v77
	v_cvt_pk_bf16_f32 v76, v80, v81
	v_cvt_pk_bf16_f32 v77, v82, v83
	global_store_dwordx4 v[110:111], v[74:77], off offset:1024
	s_cbranch_scc1 .LBB0_1585

.LBB0_1855:
	s_mov_b64 s[10:11], 0x80
	s_lshl_b32 s5, s5, 5
	s_add_i32 m0, s35, 0x18000
	v_lshl_add_u64 v[6:7], v[6:7], 0, s[10:11]
	s_lshl_b32 s14, s0, 13
	s_and_b32 s5, s5, 0x60
	s_waitcnt vmcnt(2)
	s_barrier
	global_load_lds_dwordx4 v[6:7], off
	v_lshl_add_u64 v[2:3], v[2:3], 0, s[10:11]
	s_add_i32 m0, s35, 0x1a000
	s_add_i32 s42, s35, 0x8000
	s_add_i32 s43, s35, 0xa000
	global_load_lds_dwordx4 v[2:3], off
	v_lshl_add_u64 v[0:1], v[0:1], 0, s[10:11]
	s_mov_b32 m0, s42
	s_add_u32 s12, s28, 0xb0080
	global_load_lds_dwordx4 v[0:1], off
	v_lshl_add_u64 v[0:1], v[4:5], 0, s[10:11]
	s_mov_b32 m0, s43
	s_addc_u32 s13, s29, 0
	global_load_lds_dwordx4 v[0:1], off
	s_add_i32 m0, s35, 0x1c000
	v_lshl_add_u64 v[0:1], s[12:13], 0, v[158:159]
	global_load_lds_dwordx4 v[0:1], off
	v_lshl_add_u64 v[0:1], s[12:13], 0, v[162:163]
	s_add_i32 m0, s35, 0x1e000
	s_waitcnt vmcnt(0)
	v_lshl_or_b32 v142, s0, 6, v169
	global_load_lds_dwordx4 v[0:1], off
	s_movk_i32 s0, 0x3c0
	v_lshlrev_b32_e32 v1, 2, v169
	v_and_or_b32 v0, v155, s0, v207
	v_and_b32_e32 v1, 32, v1
	v_bitop3_b32 v0, v0, s14, v1 bitop3:0xde
	s_waitcnt vmcnt(6)
	s_cmpk_lt_u32 s4, 0x100
	v_add_u16_e32 v1, v173, v179
	v_lshl_or_b32 v143, s5, 7, v208
	s_cselect_b64 s[12:13], -1, 0
	v_lshrrev_b16_e32 v1, 1, v1
	s_add_i32 s45, 0, 0x10000
	s_add_i32 s46, 0, 0x14000
	s_sext_i32_i8 s54, s1
	s_ashr_i32 s44, s3, 31
	v_or_b32_e32 v144, s5, v206
	v_add_lshl_u32 v128, v204, v1, 1
	v_mov_b32_e32 v129, v159
	v_add_lshl_u32 v130, v205, v1, 1
	v_mov_b32_e32 v131, v159
	v_mov_b64_e32 v[132:133], 0x100
	v_mov_b64_e32 v[134:135], 0xff
	v_add_u32_e32 v145, s45, v143
	v_add_u32_e32 v146, s46, v143
	v_add_u32_e32 v147, 0, v0
	s_mov_b64 s[14:15], 0x80000
	s_mov_b32 s47, 0x80000
	s_mov_b64 s[18:19], 0x90000
	s_mov_b32 s48, 0x90000
	s_mov_b64 s[20:21], 0xa0000
	s_mov_b32 s49, 0xa0000
	s_mov_b32 s50, 0xb0000
	s_barrier
	s_branch .LBB0_1858
	s_nop 0
	s_nop 0
	s_nop 0
	s_nop 0
	s_nop 0
	s_nop 0
	s_nop 0
